# epilogue-operand LDS prefetch extended to the w_out phase (x pieces) in addition to w_mo / w_down (H pieces)
# baseline (speedup 1.0000x reference)
.LBB0_893:
	s_cmp_lg_u32 s63, 3
	s_cbranch_scc1 .Lhp_nox
	v_readlane_b32 s0, v254, 56
	v_readlane_b32 s1, v254, 57
	s_load_dwordx2 s[0:1], s[0:1], 0x0
	s_waitcnt lgkmcnt(0)
	v_writelane_b32 v143, s0, 0
	v_writelane_b32 v143, s1, 1

.LBB0_894:
	s_add_i32 s6, s2, 2
	s_add_u32 s7, s64, s0
	s_addc_u32 s3, s65, s1
	s_add_u32 s8, s66, s0
	s_addc_u32 s9, s67, s1
	s_add_i32 s33, 0, 0x10000
	v_add_u32_e32 v160, s33, v165
	ds_read_b128 v[148:151], v160
	ds_read_b128 v[152:155], v160 offset:1024
	ds_read_b128 v[156:159], v160 offset:2048
	ds_read_b128 v[160:163], v160 offset:3072
	s_cmp_eq_u32 s92, s2
	s_cselect_b32 s2, s72, s7
	s_cselect_b32 s3, s73, s3
	s_cselect_b32 s9, s75, s9
	s_cselect_b32 s8, s74, s8
	s_cbranch_scc0 .Lhp_skip
	s_cmp_lg_u64 s[70:71], 0
	s_cbranch_scc1 .Lhp_skip
	s_cmp_eq_u32 s63, 3
	s_cbranch_scc1 .Lhp_x
	s_cmp_eq_u32 s63, 7
	s_cbranch_scc1 .Lhp_on
	s_cmp_lg_u32 s63, 9
	s_cbranch_scc1 .Lhp_skip
.Lhp_on:
	s_mov_b32 s32, 1
	v_add_u32_e32 v142, v168, v167
	s_lshl_b32 s72, s81, 11
	s_lshl_b32 s73, s62, 1
	v_lshlrev_b32_e32 v142, 1, v142
	s_add_u32 s72, s72, s73
	v_lshl_add_u32 v142, v166, 11, v142
	s_add_u32 s72, s46, s72
	s_addc_u32 s73, s47, 0
	s_branch .Lhp_skip
.Lhp_x:
	s_mov_b32 s32, 2
	v_readlane_b32 s72, v143, 0
	v_readlane_b32 s73, v143, 1
	v_add_u32_e32 v142, v168, v167
	s_lshl_b32 s74, s81, 12
	s_lshl_b32 s75, s62, 2
	v_lshlrev_b32_e32 v142, 2, v142
	s_add_u32 s74, s74, s75
	v_lshl_add_u32 v142, v166, 12, v142
	s_add_u32 s72, s72, s74
	s_addc_u32 s73, s73, 0
.Lhp_skip:
	v_lshl_add_u64 v[232:233], s[64:65], 0, v[132:133]
	s_add_i32 m0, s84, 0xc000
	ds_read_b128 v[196:199], v195
	ds_read_b128 v[200:203], v195 offset:1024
	ds_read_b128 v[204:207], v195 offset:2048
	ds_read_b128 v[208:211], v195 offset:3072
	ds_read_b128 v[212:215], v195 offset:4096
	ds_read_b128 v[216:219], v195 offset:5120
	ds_read_b128 v[220:223], v195 offset:6144
	ds_read_b128 v[224:227], v195 offset:7168
	global_load_lds_dwordx4 v[232:233], off
	v_lshl_add_u64 v[232:233], s[64:65], 0, v[134:135]
	s_add_i32 m0, s84, 0xe000
	s_nop 0
	global_load_lds_dwordx4 v[232:233], off
	s_waitcnt lgkmcnt(8)
	s_barrier
	s_waitcnt lgkmcnt(0)
	s_setprio 1
	s_waitcnt lgkmcnt(0)
	v_mfma_f32_16x16x32_bf16 v[128:131], v[148:151], v[196:199], v[128:131]
	v_mfma_f32_16x16x32_bf16 v[124:127], v[156:159], v[196:199], v[124:127]
	v_mfma_f32_16x16x32_bf16 v[108:111], v[148:151], v[204:207], v[108:111]
	v_mfma_f32_16x16x32_bf16 v[100:103], v[156:159], v[204:207], v[100:103]
	v_mfma_f32_16x16x32_bf16 v[88:91], v[148:151], v[212:215], v[88:91]
	v_mfma_f32_16x16x32_bf16 v[84:87], v[156:159], v[212:215], v[84:87]
	v_mfma_f32_16x16x32_bf16 v[56:59], v[148:151], v[220:223], v[56:59]
	v_mfma_f32_16x16x32_bf16 v[44:47], v[156:159], v[220:223], v[44:47]
	v_mfma_f32_16x16x32_bf16 v[128:131], v[152:155], v[200:203], v[128:131]
	v_mfma_f32_16x16x32_bf16 v[124:127], v[160:163], v[200:203], v[124:127]
	v_mfma_f32_16x16x32_bf16 v[108:111], v[152:155], v[208:211], v[108:111]
	v_mfma_f32_16x16x32_bf16 v[100:103], v[160:163], v[208:211], v[100:103]
	v_mfma_f32_16x16x32_bf16 v[88:91], v[152:155], v[216:219], v[88:91]
	v_mfma_f32_16x16x32_bf16 v[84:87], v[160:163], v[216:219], v[84:87]
	v_mfma_f32_16x16x32_bf16 v[56:59], v[152:155], v[224:227], v[56:59]
	v_mfma_f32_16x16x32_bf16 v[44:47], v[160:163], v[224:227], v[44:47]
	s_setprio 0
	s_barrier
	s_add_i32 s7, 0, 0x14000
	s_add_i32 s33, s33, s87
	v_lshl_add_u64 v[248:249], s[8:9], 0, v[138:139]
	s_add_u32 s8, s8, s34
	v_add_u32_e32 v244, s7, v165
	s_mov_b32 m0, s33
	s_addc_u32 s9, s9, s35
	ds_read_b128 v[232:235], v244
	ds_read_b128 v[236:239], v244 offset:1024
	ds_read_b128 v[240:243], v244 offset:2048
	ds_read_b128 v[244:247], v244 offset:3072
	s_cmp_eq_u32 s32, 0
	s_cbranch_scc1 .Lhp_o3
	global_load_lds_dwordx4 v142, s[72:73]
	s_cmp_eq_u32 s32, 1
	s_cbranch_scc1 .Lhp_h3
	s_add_u32 s72, s72, 0x10
	s_addc_u32 s73, s73, 0
	s_branch .Lhp_e3
.Lhp_h3:
	s_add_u32 s72, s72, 0x100
	s_addc_u32 s73, s73, 0
	s_branch .Lhp_e3

.Lhp_e3:
	v_lshl_add_u64 v[250:251], s[8:9], 0, v[138:139]
	s_add_i32 m0, s33, 0x2000
	s_nop 0
	s_cmp_eq_u32 s32, 0
	s_cbranch_scc1 .Lhp_o4
	global_load_lds_dwordx4 v142, s[72:73]
	s_cmp_eq_u32 s32, 1
	s_cbranch_scc1 .Lhp_h4
	s_add_u32 s72, s72, 0x1f0
	s_addc_u32 s73, s73, 0
	s_branch .Lhp_e4
.Lhp_h4:
	s_add_u32 s72, s72, 0x7f00
	s_addc_u32 s73, s73, 0
	s_branch .Lhp_e4

.Lhp_e4:
	s_waitcnt vmcnt(10)
	s_barrier
	s_waitcnt lgkmcnt(0)
	s_setprio 1
	s_waitcnt lgkmcnt(0)
	v_mfma_f32_16x16x32_bf16 v[120:123], v[232:235], v[196:199], v[120:123]
	v_mfma_f32_16x16x32_bf16 v[116:119], v[240:243], v[196:199], v[116:119]
	v_mfma_f32_16x16x32_bf16 v[112:115], v[232:235], v[204:207], v[112:115]
	v_mfma_f32_16x16x32_bf16 v[104:107], v[240:243], v[204:207], v[104:107]
	v_mfma_f32_16x16x32_bf16 v[96:99], v[232:235], v[212:215], v[96:99]
	v_mfma_f32_16x16x32_bf16 v[92:95], v[240:243], v[212:215], v[92:95]
	v_mfma_f32_16x16x32_bf16 v[80:83], v[232:235], v[220:223], v[80:83]
	v_mfma_f32_16x16x32_bf16 v[76:79], v[240:243], v[220:223], v[76:79]
	v_mfma_f32_16x16x32_bf16 v[120:123], v[236:239], v[200:203], v[120:123]
	v_mfma_f32_16x16x32_bf16 v[116:119], v[244:247], v[200:203], v[116:119]
	v_mfma_f32_16x16x32_bf16 v[112:115], v[236:239], v[208:211], v[112:115]
	v_mfma_f32_16x16x32_bf16 v[104:107], v[244:247], v[208:211], v[104:107]
	v_mfma_f32_16x16x32_bf16 v[96:99], v[236:239], v[216:219], v[96:99]
	v_mfma_f32_16x16x32_bf16 v[92:95], v[244:247], v[216:219], v[92:95]
	v_mfma_f32_16x16x32_bf16 v[80:83], v[236:239], v[224:227], v[80:83]
	v_mfma_f32_16x16x32_bf16 v[76:79], v[244:247], v[224:227], v[76:79]
	s_setprio 0
	s_add_u32 s76, s2, s30
	s_mov_b32 m0, s84
	v_lshl_add_u64 v[250:251], s[2:3], 0, v[140:141]
	s_addc_u32 s77, s3, s31
	s_barrier
	ds_read_b128 v[196:199], v195 offset:16384
	ds_read_b128 v[200:203], v195 offset:17408
	ds_read_b128 v[204:207], v195 offset:18432
	ds_read_b128 v[208:211], v195 offset:19456
	ds_read_b128 v[212:215], v195 offset:20480
	ds_read_b128 v[216:219], v195 offset:21504
	ds_read_b128 v[220:223], v195 offset:22528
	ds_read_b128 v[224:227], v195 offset:23552
	s_cmp_eq_u32 s32, 0
	s_cbranch_scc1 .Lhp_o5
	global_load_lds_dwordx4 v142, s[72:73]
	s_cmp_eq_u32 s32, 1
	s_cbranch_scc1 .Lhp_h5
	s_add_u32 s72, s72, 0x10
	s_addc_u32 s73, s73, 0
	s_branch .Lhp_e5

.Lhp_e5:
	v_lshl_add_u64 v[252:253], s[76:77], 0, v[140:141]
	s_mov_b32 m0, s93
	s_nop 0
	s_cmp_eq_u32 s32, 0
	s_cbranch_scc1 .Lhp_o6
	global_load_lds_dwordx4 v142, s[72:73]
	s_cmp_eq_u32 s32, 1
	s_cbranch_scc1 .Lhp_h6
	s_add_u32 s72, s72, 0xfdf0
	s_addc_u32 s73, s73, 0
	s_branch .Lhp_e6

.Lhp_e6:
	s_barrier
	s_waitcnt lgkmcnt(0)
	s_setprio 1
	s_waitcnt lgkmcnt(0)
	v_mfma_f32_16x16x32_bf16 v[64:67], v[148:151], v[196:199], v[64:67]
	v_mfma_f32_16x16x32_bf16 v[60:63], v[156:159], v[196:199], v[60:63]
	v_mfma_f32_16x16x32_bf16 v[40:43], v[148:151], v[204:207], v[40:43]
	v_mfma_f32_16x16x32_bf16 v[36:39], v[156:159], v[204:207], v[36:39]
	v_mfma_f32_16x16x32_bf16 v[22:25], v[148:151], v[212:215], v[22:25]
	v_mfma_f32_16x16x32_bf16 v[18:21], v[156:159], v[212:215], v[18:21]
	v_mfma_f32_16x16x32_bf16 v[6:9], v[148:151], v[220:223], v[6:9]
	v_mfma_f32_16x16x32_bf16 v[2:5], v[156:159], v[220:223], v[2:5]
	v_mfma_f32_16x16x32_bf16 v[64:67], v[152:155], v[200:203], v[64:67]
	v_mfma_f32_16x16x32_bf16 v[60:63], v[160:163], v[200:203], v[60:63]
	v_mfma_f32_16x16x32_bf16 v[40:43], v[152:155], v[208:211], v[40:43]
	v_mfma_f32_16x16x32_bf16 v[36:39], v[160:163], v[208:211], v[36:39]
	v_mfma_f32_16x16x32_bf16 v[22:25], v[152:155], v[216:219], v[22:25]
	v_mfma_f32_16x16x32_bf16 v[18:21], v[160:163], v[216:219], v[18:21]
	v_mfma_f32_16x16x32_bf16 v[6:9], v[152:155], v[224:227], v[6:9]
	v_mfma_f32_16x16x32_bf16 v[2:5], v[160:163], v[224:227], v[2:5]
	s_setprio 0
	s_barrier
	s_add_u32 s2, s8, s34
	s_addc_u32 s3, s9, s35
	s_add_i32 s7, s7, s87
	s_add_u32 s8, s2, s34
	v_lshl_add_u64 v[148:149], s[2:3], 0, v[138:139]
	s_mov_b32 m0, s7
	s_addc_u32 s9, s3, s35
	s_cmp_eq_u32 s32, 0
	s_cbranch_scc1 .Lhp_o7
	global_load_lds_dwordx4 v142, s[72:73]
	s_cmp_eq_u32 s32, 1
	s_cbranch_scc1 .Lhp_h7
	s_add_u32 s72, s72, 0x10
	s_addc_u32 s73, s73, 0
	s_branch .Lhp_e7

.Lhp_e7:
	v_lshl_add_u64 v[252:253], s[8:9], 0, v[138:139]
	s_add_i32 m0, s7, 0x2000
	s_nop 0
	s_cmp_eq_u32 s32, 0
	s_cbranch_scc1 .Lhp_o8
	global_load_lds_dwordx4 v142, s[72:73]
	s_cmp_eq_u32 s32, 1
	s_cbranch_scc1 .Lhp_h8
	s_add_u32 s72, s72, 0x1f0
	s_addc_u32 s73, s73, 0
	s_branch .Lhp_e8

.Lhp_e8:
	s_waitcnt vmcnt(8)
	s_barrier
	s_setprio 1
	v_mfma_f32_16x16x32_bf16 v[72:75], v[232:235], v[196:199], v[72:75]
	v_mfma_f32_16x16x32_bf16 v[68:71], v[240:243], v[196:199], v[68:71]
	v_mfma_f32_16x16x32_bf16 v[52:55], v[232:235], v[204:207], v[52:55]
	v_mfma_f32_16x16x32_bf16 v[48:51], v[240:243], v[204:207], v[48:51]
	v_mfma_f32_16x16x32_bf16 v[32:35], v[232:235], v[212:215], v[32:35]
	v_mfma_f32_16x16x32_bf16 v[28:31], v[240:243], v[212:215], v[28:31]
	v_mfma_f32_16x16x32_bf16 v[14:17], v[232:235], v[220:223], v[14:17]
	v_mfma_f32_16x16x32_bf16 v[10:13], v[240:243], v[220:223], v[10:13]
	v_mfma_f32_16x16x32_bf16 v[72:75], v[236:239], v[200:203], v[72:75]
	v_mfma_f32_16x16x32_bf16 v[68:71], v[244:247], v[200:203], v[68:71]
	v_mfma_f32_16x16x32_bf16 v[52:55], v[236:239], v[208:211], v[52:55]
	v_mfma_f32_16x16x32_bf16 v[48:51], v[244:247], v[208:211], v[48:51]
	v_mfma_f32_16x16x32_bf16 v[32:35], v[236:239], v[216:219], v[32:35]
	v_mfma_f32_16x16x32_bf16 v[28:31], v[244:247], v[216:219], v[28:31]
	v_mfma_f32_16x16x32_bf16 v[14:17], v[236:239], v[224:227], v[14:17]
	v_mfma_f32_16x16x32_bf16 v[10:13], v[244:247], v[224:227], v[10:13]
	s_setprio 0
	s_add_i32 s7, 0, 0x18000
	v_add_u32_e32 v160, s7, v165
	s_barrier
	ds_read_b128 v[148:151], v160
	ds_read_b128 v[152:155], v160 offset:1024
	ds_read_b128 v[156:159], v160 offset:2048
	ds_read_b128 v[160:163], v160 offset:3072
	s_add_u32 s8, s76, s30
	s_addc_u32 s9, s77, s31
	s_add_u32 s76, s8, s30
	s_mov_b32 m0, s28
	v_lshl_add_u64 v[232:233], s[8:9], 0, v[140:141]
	s_addc_u32 s77, s9, s31
	ds_read_b128 v[196:199], v195 offset:32768
	ds_read_b128 v[200:203], v195 offset:33792
	ds_read_b128 v[204:207], v195 offset:34816
	ds_read_b128 v[208:211], v195 offset:35840
	ds_read_b128 v[212:215], v195 offset:36864
	ds_read_b128 v[216:219], v195 offset:37888
	ds_read_b128 v[220:223], v195 offset:38912
	ds_read_b128 v[224:227], v195 offset:39936
	s_cmp_eq_u32 s32, 0
	s_cbranch_scc1 .Lhp_o9
	global_load_lds_dwordx4 v142, s[72:73]
	s_cmp_eq_u32 s32, 1
	s_cbranch_scc1 .Lhp_h9
	s_add_u32 s72, s72, 0x10
	s_addc_u32 s73, s73, 0
	s_branch .Lhp_e9

.Lhp_e9:
	v_lshl_add_u64 v[232:233], s[76:77], 0, v[140:141]
	s_mov_b32 m0, s29
	s_nop 0
	s_cmp_eq_u32 s32, 0
	s_cbranch_scc1 .Lhp_o10
	global_load_lds_dwordx4 v142, s[72:73]
	s_cmp_eq_u32 s32, 1
	s_cbranch_scc1 .Lhp_h10
	s_add_u32 s72, s72, 0xfdf0
	s_addc_u32 s73, s73, 0
	s_branch .Lhp_e10
.Lhp_h10:
	s_add_u32 s72, s72, 0x27f00
	s_addc_u32 s73, s73, 0
	s_branch .Lhp_e10

.Lhp_e10:
	s_waitcnt lgkmcnt(8)
	s_barrier
	s_waitcnt lgkmcnt(0)
	s_setprio 1
	s_waitcnt lgkmcnt(0)
	v_mfma_f32_16x16x32_bf16 v[128:131], v[148:151], v[196:199], v[128:131]
	v_mfma_f32_16x16x32_bf16 v[124:127], v[156:159], v[196:199], v[124:127]
	v_mfma_f32_16x16x32_bf16 v[108:111], v[148:151], v[204:207], v[108:111]
	v_mfma_f32_16x16x32_bf16 v[100:103], v[156:159], v[204:207], v[100:103]
	v_mfma_f32_16x16x32_bf16 v[88:91], v[148:151], v[212:215], v[88:91]
	v_mfma_f32_16x16x32_bf16 v[84:87], v[156:159], v[212:215], v[84:87]
	v_mfma_f32_16x16x32_bf16 v[56:59], v[148:151], v[220:223], v[56:59]
	v_mfma_f32_16x16x32_bf16 v[44:47], v[156:159], v[220:223], v[44:47]
	v_mfma_f32_16x16x32_bf16 v[128:131], v[152:155], v[200:203], v[128:131]
	v_mfma_f32_16x16x32_bf16 v[124:127], v[160:163], v[200:203], v[124:127]
	v_mfma_f32_16x16x32_bf16 v[108:111], v[152:155], v[208:211], v[108:111]
	v_mfma_f32_16x16x32_bf16 v[100:103], v[160:163], v[208:211], v[100:103]
	v_mfma_f32_16x16x32_bf16 v[88:91], v[152:155], v[216:219], v[88:91]
	v_mfma_f32_16x16x32_bf16 v[84:87], v[160:163], v[216:219], v[84:87]
	v_mfma_f32_16x16x32_bf16 v[56:59], v[152:155], v[224:227], v[56:59]
	v_mfma_f32_16x16x32_bf16 v[44:47], v[160:163], v[224:227], v[44:47]
	s_setprio 0
	s_barrier
	s_add_i32 s33, 0, 0x1c000
	s_add_i32 s7, s7, s87
	s_add_u32 s2, s2, s94
	v_add_u32_e32 v244, s33, v165
	v_lshl_add_u64 v[248:249], v[248:249], 0, s[16:17]
	s_mov_b32 m0, s7
	s_addc_u32 s3, s3, s95
	ds_read_b128 v[232:235], v244
	ds_read_b128 v[236:239], v244 offset:1024
	ds_read_b128 v[240:243], v244 offset:2048
	ds_read_b128 v[244:247], v244 offset:3072
	s_cmp_eq_u32 s32, 0
	s_cbranch_scc1 .Lhp_o11
	global_load_lds_dwordx4 v142, s[72:73]
	s_cmp_eq_u32 s32, 1
	s_cbranch_scc1 .Lhp_h11
	s_add_u32 s72, s72, 0x10
	s_addc_u32 s73, s73, 0
	s_branch .Lhp_e11

.Lhp_e11:
	v_lshl_add_u64 v[248:249], s[2:3], 0, v[138:139]
	v_lshl_add_u64 v[248:249], v[248:249], 0, s[16:17]
	s_add_i32 m0, s7, 0x2000
	s_nop 0
	s_cmp_eq_u32 s32, 0
	s_cbranch_scc1 .Lhp_o12
	global_load_lds_dwordx4 v142, s[72:73]
	s_cmp_eq_u32 s32, 1
	s_cbranch_scc1 .Lhp_h12
	s_add_u32 s72, s72, 0x1f0
	s_addc_u32 s73, s73, 0
	s_branch .Lhp_e12

.Lhp_e12:
	s_waitcnt vmcnt(10)
	s_barrier
	s_waitcnt lgkmcnt(0)
	s_setprio 1
	s_waitcnt lgkmcnt(0)
	v_mfma_f32_16x16x32_bf16 v[120:123], v[232:235], v[196:199], v[120:123]
	v_mfma_f32_16x16x32_bf16 v[116:119], v[240:243], v[196:199], v[116:119]
	v_mfma_f32_16x16x32_bf16 v[112:115], v[232:235], v[204:207], v[112:115]
	v_mfma_f32_16x16x32_bf16 v[104:107], v[240:243], v[204:207], v[104:107]
	v_mfma_f32_16x16x32_bf16 v[96:99], v[232:235], v[212:215], v[96:99]
	v_mfma_f32_16x16x32_bf16 v[92:95], v[240:243], v[212:215], v[92:95]
	v_mfma_f32_16x16x32_bf16 v[80:83], v[232:235], v[220:223], v[80:83]
	v_mfma_f32_16x16x32_bf16 v[76:79], v[240:243], v[220:223], v[76:79]
	v_mfma_f32_16x16x32_bf16 v[120:123], v[236:239], v[200:203], v[120:123]
	v_mfma_f32_16x16x32_bf16 v[116:119], v[244:247], v[200:203], v[116:119]
	v_mfma_f32_16x16x32_bf16 v[112:115], v[236:239], v[208:211], v[112:115]
	v_mfma_f32_16x16x32_bf16 v[104:107], v[244:247], v[208:211], v[104:107]
	v_mfma_f32_16x16x32_bf16 v[96:99], v[236:239], v[216:219], v[96:99]
	v_mfma_f32_16x16x32_bf16 v[92:95], v[244:247], v[216:219], v[92:95]
	v_mfma_f32_16x16x32_bf16 v[80:83], v[236:239], v[224:227], v[80:83]
	v_mfma_f32_16x16x32_bf16 v[76:79], v[244:247], v[224:227], v[76:79]
	s_setprio 0
	s_add_u32 s8, s8, s96
	s_mov_b32 m0, s40
	v_lshl_add_u64 v[248:249], v[250:251], 0, s[16:17]
	s_addc_u32 s9, s9, s97
	s_barrier
	ds_read_b128 v[196:199], v195 offset:49152
	ds_read_b128 v[200:203], v195 offset:50176
	ds_read_b128 v[204:207], v195 offset:51200
	ds_read_b128 v[208:211], v195 offset:52224
	ds_read_b128 v[212:215], v195 offset:53248
	ds_read_b128 v[216:219], v195 offset:54272
	ds_read_b128 v[220:223], v195 offset:55296
	ds_read_b128 v[224:227], v195 offset:56320
	s_cmp_eq_u32 s32, 0
	s_cbranch_scc1 .Lhp_o13
	global_load_lds_dwordx4 v142, s[72:73]
	s_cmp_eq_u32 s32, 1
	s_cbranch_scc1 .Lhp_h13
	s_add_u32 s72, s72, 0x10
	s_addc_u32 s73, s73, 0
	s_branch .Lhp_e13

.Lhp_e13:
	v_lshl_add_u64 v[248:249], s[8:9], 0, v[140:141]
	v_lshl_add_u64 v[248:249], v[248:249], 0, s[16:17]
	s_mov_b32 m0, s41
	s_nop 0
	s_cmp_eq_u32 s32, 0
	s_cbranch_scc1 .Lhp_o14
	global_load_lds_dwordx4 v142, s[72:73]
	s_cmp_eq_u32 s32, 1
	s_cbranch_scc1 .Lhp_h14
	s_add_u32 s72, s72, 0xfdf0
	s_addc_u32 s73, s73, 0
	s_branch .Lhp_e14

.Lhp_e14:
	s_barrier
	s_waitcnt lgkmcnt(0)
	s_setprio 1
	s_waitcnt lgkmcnt(0)
	v_mfma_f32_16x16x32_bf16 v[64:67], v[148:151], v[196:199], v[64:67]
	v_mfma_f32_16x16x32_bf16 v[60:63], v[156:159], v[196:199], v[60:63]
	v_mfma_f32_16x16x32_bf16 v[40:43], v[148:151], v[204:207], v[40:43]
	v_mfma_f32_16x16x32_bf16 v[36:39], v[156:159], v[204:207], v[36:39]
	v_mfma_f32_16x16x32_bf16 v[22:25], v[148:151], v[212:215], v[22:25]
	v_mfma_f32_16x16x32_bf16 v[18:21], v[156:159], v[212:215], v[18:21]
	v_mfma_f32_16x16x32_bf16 v[6:9], v[148:151], v[220:223], v[6:9]
	v_mfma_f32_16x16x32_bf16 v[2:5], v[156:159], v[220:223], v[2:5]
	v_mfma_f32_16x16x32_bf16 v[64:67], v[152:155], v[200:203], v[64:67]
	v_mfma_f32_16x16x32_bf16 v[60:63], v[160:163], v[200:203], v[60:63]
	v_mfma_f32_16x16x32_bf16 v[40:43], v[152:155], v[208:211], v[40:43]
	v_mfma_f32_16x16x32_bf16 v[36:39], v[160:163], v[208:211], v[36:39]
	v_mfma_f32_16x16x32_bf16 v[22:25], v[152:155], v[216:219], v[22:25]
	v_mfma_f32_16x16x32_bf16 v[18:21], v[160:163], v[216:219], v[18:21]
	v_mfma_f32_16x16x32_bf16 v[6:9], v[152:155], v[224:227], v[6:9]
	v_mfma_f32_16x16x32_bf16 v[2:5], v[160:163], v[224:227], v[2:5]
	s_setprio 0
	s_barrier
	s_add_u32 s2, s2, s34
	s_addc_u32 s3, s3, s35
	v_lshl_add_u64 v[148:149], s[2:3], 0, v[138:139]
	s_add_i32 s2, s33, s87
	v_lshl_add_u64 v[148:149], v[148:149], 0, s[16:17]
	s_mov_b32 m0, s2
	s_nop 0
	s_cmp_eq_u32 s32, 0
	s_cbranch_scc1 .Lhp_o15
	global_load_lds_dwordx4 v142, s[72:73]
	s_cmp_eq_u32 s32, 1
	s_cbranch_scc1 .Lhp_h15
	s_add_u32 s72, s72, 0x10
	s_addc_u32 s73, s73, 0
	s_branch .Lhp_e15

.LBB0_928:
	s_and_b64 vcc, exec, s[2:3]
	s_cbranch_vccz .LBB0_1042
	s_cmp_gt_i32 s63, 1
	s_mov_b64 s[0:1], -1
	s_cbranch_scc0 .LBB0_951
	s_cmp_gt_i32 s63, 2
	s_cbranch_scc0 .LBB0_948
	v_readlane_b32 s0, v254, 56
	v_readlane_b32 s1, v254, 57
	s_load_dwordx4 s[0:3], s[0:1], 0x0
	v_ashrrev_i32_e32 v149, 31, v148
	v_add_u32_e32 v134, v132, v167
	v_ashrrev_i32_e32 v135, 31, v134
	v_lshlrev_b64 v[250:251], 11, v[148:149]
	v_lshl_add_u64 v[250:251], s[46:47], 0, v[250:251]
	v_lshl_add_u64 v[250:251], v[134:135], 1, v[250:251]
	v_lshl_add_u64 v[252:253], v[148:149], 2, s[50:51]
	v_xor_b32_e32 v132, 16, v230
	v_xor_b32_e32 v133, 32, v230
	v_lshlrev_b32_e32 v132, 2, v132
	v_lshlrev_b32_e32 v133, 2, v133
	s_waitcnt lgkmcnt(0)
	s_cmpk_lt_i32 s81, 0x4000
	s_cselect_b32 s0, s0, s2
	s_cselect_b32 s1, s1, s3
	s_cselect_b32 s6, 0, 0x4000
	v_subrev_u32_e32 v248, s6, v148
	v_ashrrev_i32_e32 v249, 31, v248
	v_lshlrev_b64 v[248:249], 12, v[248:249]
	v_lshl_add_u64 v[248:249], s[0:1], 0, v[248:249]
	v_lshl_add_u64 v[248:249], v[134:135], 2, v[248:249]
	s_cmp_eq_u32 s32, 0
	s_cbranch_scc1 .Lout_gl
	s_mov_b32 s32, 0
	s_mov_b64 s[2:3], 0x30000
	v_lshl_add_u64 v[248:249], v[248:249], 0, s[2:3]
	s_waitcnt vmcnt(0)
	global_load_dwordx4 v[156:159], v[248:249], off offset:512 nt
	global_load_dwordx4 v[160:163], v[248:249], off offset:528 nt
	s_mov_b64 s[2:3], 0x50000
	v_lshl_add_u64 v[248:249], v[248:249], 0, s[2:3]
	v_lshlrev_b32_e32 v134, 4, v174
	v_add_u32_e32 v135, 0x10000, v134
	ds_read_b128 v[196:199], v135
	ds_read_b128 v[200:203], v135 offset:8192
	ds_read_b128 v[204:207], v134
	ds_read_b128 v[208:211], v134 offset:8192
	ds_read_b128 v[212:215], v135 offset:16384
	ds_read_b128 v[216:219], v135 offset:24576
	ds_read_b128 v[220:223], v134 offset:16384
	ds_read_b128 v[224:227], v134 offset:24576
	ds_read_b128 v[232:235], v135 offset:32768
	ds_read_b128 v[236:239], v135 offset:40960
	ds_read_b128 v[240:243], v134 offset:32768
	ds_read_b128 v[244:247], v134 offset:40960
	ds_read_b128 v[148:151], v135 offset:49152
	ds_read_b128 v[152:155], v135 offset:57344
	s_waitcnt lgkmcnt(0)
	s_branch .Lout_go
.Lout_gl:
	global_load_dwordx4 v[196:199], v[248:249], off nt
	global_load_dwordx4 v[200:203], v[248:249], off offset:16 nt
	global_load_dwordx4 v[204:207], v[248:249], off offset:512 nt
	global_load_dwordx4 v[208:211], v[248:249], off offset:528 nt
	s_mov_b64 s[2:3], 0x10000
	v_lshl_add_u64 v[248:249], v[248:249], 0, s[2:3]
	global_load_dwordx4 v[212:215], v[248:249], off nt
	global_load_dwordx4 v[216:219], v[248:249], off offset:16 nt
	global_load_dwordx4 v[220:223], v[248:249], off offset:512 nt
	global_load_dwordx4 v[224:227], v[248:249], off offset:528 nt
	v_lshl_add_u64 v[248:249], v[248:249], 0, s[2:3]
	global_load_dwordx4 v[232:235], v[248:249], off nt
	global_load_dwordx4 v[236:239], v[248:249], off offset:16 nt
	global_load_dwordx4 v[240:243], v[248:249], off offset:512 nt
	global_load_dwordx4 v[244:247], v[248:249], off offset:528 nt
	v_lshl_add_u64 v[248:249], v[248:249], 0, s[2:3]
	global_load_dwordx4 v[148:151], v[248:249], off nt
	global_load_dwordx4 v[152:155], v[248:249], off offset:16 nt
	global_load_dwordx4 v[156:159], v[248:249], off offset:512 nt
	global_load_dwordx4 v[160:163], v[248:249], off offset:528 nt
	s_mov_b64 s[2:3], 0x50000
	v_lshl_add_u64 v[248:249], v[248:249], 0, s[2:3]
.Lout_go:
	s_waitcnt vmcnt(12)
	v_pk_add_f32 v[128:129], v[128:129], v[196:197]
	v_pk_add_f32 v[130:131], v[130:131], v[198:199]
	v_pk_add_f32 v[124:125], v[124:125], v[200:201]
	v_pk_add_f32 v[126:127], v[126:127], v[202:203]
	v_pk_add_f32 v[120:121], v[120:121], v[204:205]
	v_pk_add_f32 v[122:123], v[122:123], v[206:207]
	v_pk_add_f32 v[116:117], v[116:117], v[208:209]
	v_pk_add_f32 v[118:119], v[118:119], v[210:211]
	v_mul_f32_e32 v196, v129, v129
	v_mul_f32_e32 v197, v131, v131
	v_fmac_f32_e32 v196, v128, v128
	v_fmac_f32_e32 v197, v130, v130
	v_mul_f32_e32 v198, v125, v125
	v_mul_f32_e32 v199, v127, v127
	v_add_f32_e32 v196, v196, v197
	v_fmac_f32_e32 v198, v124, v124
	v_fmac_f32_e32 v199, v126, v126
	v_cvt_pk_bf16_f32 v128, v128, v129
	v_add_f32_e32 v198, v198, v199
	v_cvt_pk_bf16_f32 v129, v130, v131
	v_add_f32_e32 v196, v196, v198
	v_cvt_pk_bf16_f32 v130, v124, v125
	v_cvt_pk_bf16_f32 v131, v126, v127
	global_store_dwordx4 v[250:251], v[128:131], off
	v_mul_f32_e32 v204, v121, v121
	v_mul_f32_e32 v205, v123, v123
	v_fmac_f32_e32 v204, v120, v120
	v_fmac_f32_e32 v205, v122, v122
	v_mul_f32_e32 v206, v117, v117
	v_mul_f32_e32 v207, v119, v119
	v_add_f32_e32 v204, v204, v205
	v_fmac_f32_e32 v206, v116, v116
	v_fmac_f32_e32 v207, v118, v118
	v_cvt_pk_bf16_f32 v120, v120, v121
	v_add_f32_e32 v206, v206, v207
	v_cvt_pk_bf16_f32 v121, v122, v123
	v_add_f32_e32 v204, v204, v206
	v_cvt_pk_bf16_f32 v122, v116, v117
	v_cvt_pk_bf16_f32 v123, v118, v119
	global_store_dwordx4 v[250:251], v[120:123], off offset:256
	v_add_f32_e32 v124, v196, v204
	global_load_dwordx4 v[196:199], v[248:249], off nt
	global_load_dwordx4 v[200:203], v[248:249], off offset:16 nt
	global_load_dwordx4 v[204:207], v[248:249], off offset:512 nt
	global_load_dwordx4 v[208:211], v[248:249], off offset:528 nt
	s_mov_b64 s[2:3], 0x10000
	v_lshl_add_u64 v[248:249], v[248:249], 0, s[2:3]
	s_mov_b64 s[6:7], 0x8000
	v_lshl_add_u64 v[250:251], v[250:251], 0, s[6:7]
	s_waitcnt vmcnt(14)
	v_pk_add_f32 v[108:109], v[108:109], v[212:213]
	v_pk_add_f32 v[110:111], v[110:111], v[214:215]
	v_pk_add_f32 v[100:101], v[100:101], v[216:217]
	v_pk_add_f32 v[102:103], v[102:103], v[218:219]
	v_pk_add_f32 v[112:113], v[112:113], v[220:221]
	v_pk_add_f32 v[114:115], v[114:115], v[222:223]
	v_pk_add_f32 v[104:105], v[104:105], v[224:225]
	v_pk_add_f32 v[106:107], v[106:107], v[226:227]
	v_mul_f32_e32 v212, v109, v109
	v_mul_f32_e32 v213, v111, v111
	v_fmac_f32_e32 v212, v108, v108
	v_fmac_f32_e32 v213, v110, v110
	v_mul_f32_e32 v214, v101, v101
	v_mul_f32_e32 v215, v103, v103
	v_add_f32_e32 v212, v212, v213
	v_fmac_f32_e32 v214, v100, v100
	v_fmac_f32_e32 v215, v102, v102
	v_cvt_pk_bf16_f32 v108, v108, v109
	v_add_f32_e32 v214, v214, v215
	v_cvt_pk_bf16_f32 v109, v110, v111
	v_add_f32_e32 v212, v212, v214
	v_cvt_pk_bf16_f32 v110, v100, v101
	v_cvt_pk_bf16_f32 v111, v102, v103
	global_store_dwordx4 v[250:251], v[108:111], off
	v_mul_f32_e32 v220, v113, v113
	v_mul_f32_e32 v221, v115, v115
	v_fmac_f32_e32 v220, v112, v112
	v_fmac_f32_e32 v221, v114, v114
	v_mul_f32_e32 v222, v105, v105
	v_mul_f32_e32 v223, v107, v107
	v_add_f32_e32 v220, v220, v221
	v_fmac_f32_e32 v222, v104, v104
	v_fmac_f32_e32 v223, v106, v106
	v_cvt_pk_bf16_f32 v112, v112, v113
	v_add_f32_e32 v222, v222, v223
	v_cvt_pk_bf16_f32 v113, v114, v115
	v_add_f32_e32 v220, v220, v222
	v_cvt_pk_bf16_f32 v114, v104, v105
	v_cvt_pk_bf16_f32 v115, v106, v107
	global_store_dwordx4 v[250:251], v[112:115], off offset:256
	v_add_f32_e32 v100, v212, v220
	global_load_dwordx4 v[212:215], v[248:249], off nt
	global_load_dwordx4 v[216:219], v[248:249], off offset:16 nt
	global_load_dwordx4 v[220:223], v[248:249], off offset:512 nt
	global_load_dwordx4 v[224:227], v[248:249], off offset:528 nt
	v_lshl_add_u64 v[248:249], v[248:249], 0, s[2:3]
	v_lshl_add_u64 v[250:251], v[250:251], 0, s[6:7]
	s_waitcnt vmcnt(16)
	v_pk_add_f32 v[88:89], v[88:89], v[232:233]
	v_pk_add_f32 v[90:91], v[90:91], v[234:235]
	v_pk_add_f32 v[84:85], v[84:85], v[236:237]
	v_pk_add_f32 v[86:87], v[86:87], v[238:239]
	v_pk_add_f32 v[96:97], v[96:97], v[240:241]
	v_pk_add_f32 v[98:99], v[98:99], v[242:243]
	v_pk_add_f32 v[92:93], v[92:93], v[244:245]
	v_pk_add_f32 v[94:95], v[94:95], v[246:247]
	v_mul_f32_e32 v232, v89, v89
	v_mul_f32_e32 v233, v91, v91
	v_fmac_f32_e32 v232, v88, v88
	v_fmac_f32_e32 v233, v90, v90
	v_mul_f32_e32 v234, v85, v85
	v_mul_f32_e32 v235, v87, v87
	v_add_f32_e32 v232, v232, v233
	v_fmac_f32_e32 v234, v84, v84
	v_fmac_f32_e32 v235, v86, v86
	v_cvt_pk_bf16_f32 v88, v88, v89
	v_add_f32_e32 v234, v234, v235
	v_cvt_pk_bf16_f32 v89, v90, v91
	v_add_f32_e32 v232, v232, v234
	v_cvt_pk_bf16_f32 v90, v84, v85
	v_cvt_pk_bf16_f32 v91, v86, v87
	global_store_dwordx4 v[250:251], v[88:91], off
	v_mul_f32_e32 v240, v97, v97
	v_mul_f32_e32 v241, v99, v99
	v_fmac_f32_e32 v240, v96, v96
	v_fmac_f32_e32 v241, v98, v98
	v_mul_f32_e32 v242, v93, v93
	v_mul_f32_e32 v243, v95, v95
	v_add_f32_e32 v240, v240, v241
	v_fmac_f32_e32 v242, v92, v92
	v_fmac_f32_e32 v243, v94, v94
	v_cvt_pk_bf16_f32 v96, v96, v97
	v_add_f32_e32 v242, v242, v243
	v_cvt_pk_bf16_f32 v97, v98, v99
	v_add_f32_e32 v240, v240, v242
	v_cvt_pk_bf16_f32 v98, v92, v93
	v_cvt_pk_bf16_f32 v99, v94, v95
	global_store_dwordx4 v[250:251], v[96:99], off offset:256
	v_add_f32_e32 v84, v232, v240
	global_load_dwordx4 v[232:235], v[248:249], off nt
	global_load_dwordx4 v[236:239], v[248:249], off offset:16 nt
	global_load_dwordx4 v[240:243], v[248:249], off offset:512 nt
	global_load_dwordx4 v[244:247], v[248:249], off offset:528 nt
	v_lshl_add_u64 v[248:249], v[248:249], 0, s[2:3]
	v_lshl_add_u64 v[250:251], v[250:251], 0, s[6:7]
	s_waitcnt vmcnt(18)
	v_pk_add_f32 v[56:57], v[56:57], v[148:149]
	v_pk_add_f32 v[58:59], v[58:59], v[150:151]
	v_pk_add_f32 v[44:45], v[44:45], v[152:153]
	v_pk_add_f32 v[46:47], v[46:47], v[154:155]
	v_pk_add_f32 v[80:81], v[80:81], v[156:157]
	v_pk_add_f32 v[82:83], v[82:83], v[158:159]
	v_pk_add_f32 v[76:77], v[76:77], v[160:161]
	v_pk_add_f32 v[78:79], v[78:79], v[162:163]
	v_mul_f32_e32 v148, v57, v57
	v_mul_f32_e32 v149, v59, v59
	v_fmac_f32_e32 v148, v56, v56
	v_fmac_f32_e32 v149, v58, v58
	v_mul_f32_e32 v150, v45, v45
	v_mul_f32_e32 v151, v47, v47
	v_add_f32_e32 v148, v148, v149
	v_fmac_f32_e32 v150, v44, v44
	v_fmac_f32_e32 v151, v46, v46
	v_cvt_pk_bf16_f32 v56, v56, v57
	v_add_f32_e32 v150, v150, v151
	v_cvt_pk_bf16_f32 v57, v58, v59
	v_add_f32_e32 v148, v148, v150
	v_cvt_pk_bf16_f32 v58, v44, v45
	v_cvt_pk_bf16_f32 v59, v46, v47
	global_store_dwordx4 v[250:251], v[56:59], off
	v_mul_f32_e32 v156, v81, v81
	v_mul_f32_e32 v157, v83, v83
	v_fmac_f32_e32 v156, v80, v80
	v_fmac_f32_e32 v157, v82, v82
	v_mul_f32_e32 v158, v77, v77
	v_mul_f32_e32 v159, v79, v79
	v_add_f32_e32 v156, v156, v157
	v_fmac_f32_e32 v158, v76, v76
	v_fmac_f32_e32 v159, v78, v78
	v_cvt_pk_bf16_f32 v80, v80, v81
	v_add_f32_e32 v158, v158, v159
	v_cvt_pk_bf16_f32 v81, v82, v83
	v_add_f32_e32 v156, v156, v158
	v_cvt_pk_bf16_f32 v82, v76, v77
	v_cvt_pk_bf16_f32 v83, v78, v79
	global_store_dwordx4 v[250:251], v[80:83], off offset:256
	v_add_f32_e32 v44, v148, v156
	global_load_dwordx4 v[148:151], v[248:249], off nt
	global_load_dwordx4 v[152:155], v[248:249], off offset:16 nt
	global_load_dwordx4 v[156:159], v[248:249], off offset:512 nt
	global_load_dwordx4 v[160:163], v[248:249], off offset:528 nt
	s_mov_b64 s[6:7], 0x28000
	v_lshl_add_u64 v[250:251], v[250:251], 0, s[6:7]
	s_waitcnt vmcnt(18)
	v_pk_add_f32 v[64:65], v[64:65], v[196:197]
	v_pk_add_f32 v[66:67], v[66:67], v[198:199]
	v_pk_add_f32 v[60:61], v[60:61], v[200:201]
	v_pk_add_f32 v[62:63], v[62:63], v[202:203]
	v_pk_add_f32 v[72:73], v[72:73], v[204:205]
	v_pk_add_f32 v[74:75], v[74:75], v[206:207]
	v_pk_add_f32 v[68:69], v[68:69], v[208:209]
	v_pk_add_f32 v[70:71], v[70:71], v[210:211]
	v_mul_f32_e32 v196, v65, v65
	v_mul_f32_e32 v197, v67, v67
	v_fmac_f32_e32 v196, v64, v64
	v_fmac_f32_e32 v197, v66, v66
	v_mul_f32_e32 v198, v61, v61
	v_mul_f32_e32 v199, v63, v63
	v_add_f32_e32 v196, v196, v197
	v_fmac_f32_e32 v198, v60, v60
	v_fmac_f32_e32 v199, v62, v62
	v_cvt_pk_bf16_f32 v64, v64, v65
	v_add_f32_e32 v198, v198, v199
	v_cvt_pk_bf16_f32 v65, v66, v67
	v_add_f32_e32 v196, v196, v198
	v_cvt_pk_bf16_f32 v66, v60, v61
	v_cvt_pk_bf16_f32 v67, v62, v63
	global_store_dwordx4 v[250:251], v[64:67], off
	v_mul_f32_e32 v204, v73, v73
	v_mul_f32_e32 v205, v75, v75
	v_fmac_f32_e32 v204, v72, v72
	v_fmac_f32_e32 v205, v74, v74
	v_mul_f32_e32 v206, v69, v69
	v_mul_f32_e32 v207, v71, v71
	v_add_f32_e32 v204, v204, v205
	v_fmac_f32_e32 v206, v68, v68
	v_fmac_f32_e32 v207, v70, v70
	v_cvt_pk_bf16_f32 v72, v72, v73
	v_add_f32_e32 v206, v206, v207
	v_cvt_pk_bf16_f32 v73, v74, v75
	v_add_f32_e32 v204, v204, v206
	v_cvt_pk_bf16_f32 v74, v68, v69
	v_cvt_pk_bf16_f32 v75, v70, v71
	global_store_dwordx4 v[250:251], v[72:75], off offset:256
	v_add_f32_e32 v60, v196, v204
	s_mov_b64 s[6:7], 0x8000
	v_lshl_add_u64 v[250:251], v[250:251], 0, s[6:7]
	s_waitcnt vmcnt(14)
	v_pk_add_f32 v[40:41], v[40:41], v[212:213]
	v_pk_add_f32 v[42:43], v[42:43], v[214:215]
	v_pk_add_f32 v[36:37], v[36:37], v[216:217]
	v_pk_add_f32 v[38:39], v[38:39], v[218:219]
	v_pk_add_f32 v[52:53], v[52:53], v[220:221]
	v_pk_add_f32 v[54:55], v[54:55], v[222:223]
	v_pk_add_f32 v[48:49], v[48:49], v[224:225]
	v_pk_add_f32 v[50:51], v[50:51], v[226:227]
	v_mul_f32_e32 v212, v41, v41
	v_mul_f32_e32 v213, v43, v43
	v_fmac_f32_e32 v212, v40, v40
	v_fmac_f32_e32 v213, v42, v42
	v_mul_f32_e32 v214, v37, v37
	v_mul_f32_e32 v215, v39, v39
	v_add_f32_e32 v212, v212, v213
	v_fmac_f32_e32 v214, v36, v36
	v_fmac_f32_e32 v215, v38, v38
	v_cvt_pk_bf16_f32 v40, v40, v41
	v_add_f32_e32 v214, v214, v215
	v_cvt_pk_bf16_f32 v41, v42, v43
	v_add_f32_e32 v212, v212, v214
	v_cvt_pk_bf16_f32 v42, v36, v37
	v_cvt_pk_bf16_f32 v43, v38, v39
	global_store_dwordx4 v[250:251], v[40:43], off
	v_mul_f32_e32 v220, v53, v53
	v_mul_f32_e32 v221, v55, v55
	v_fmac_f32_e32 v220, v52, v52
	v_fmac_f32_e32 v221, v54, v54
	v_mul_f32_e32 v222, v49, v49
	v_mul_f32_e32 v223, v51, v51
	v_add_f32_e32 v220, v220, v221
	v_fmac_f32_e32 v222, v48, v48
	v_fmac_f32_e32 v223, v50, v50
	v_cvt_pk_bf16_f32 v52, v52, v53
	v_add_f32_e32 v222, v222, v223
	v_cvt_pk_bf16_f32 v53, v54, v55
	v_add_f32_e32 v220, v220, v222
	v_cvt_pk_bf16_f32 v54, v48, v49
	v_cvt_pk_bf16_f32 v55, v50, v51
	global_store_dwordx4 v[250:251], v[52:55], off offset:256
	v_add_f32_e32 v36, v212, v220
	v_lshl_add_u64 v[250:251], v[250:251], 0, s[6:7]
	s_waitcnt vmcnt(10)
	v_pk_add_f32 v[22:23], v[22:23], v[232:233]
	v_pk_add_f32 v[24:25], v[24:25], v[234:235]
	v_pk_add_f32 v[18:19], v[18:19], v[236:237]
	v_pk_add_f32 v[20:21], v[20:21], v[238:239]
	v_pk_add_f32 v[32:33], v[32:33], v[240:241]
	v_pk_add_f32 v[34:35], v[34:35], v[242:243]
	v_pk_add_f32 v[28:29], v[28:29], v[244:245]
	v_pk_add_f32 v[30:31], v[30:31], v[246:247]
	v_mul_f32_e32 v232, v23, v23
	v_mul_f32_e32 v233, v25, v25
	v_fmac_f32_e32 v232, v22, v22
	v_fmac_f32_e32 v233, v24, v24
	v_mul_f32_e32 v234, v19, v19
	v_mul_f32_e32 v235, v21, v21
	v_add_f32_e32 v232, v232, v233
	v_fmac_f32_e32 v234, v18, v18
	v_fmac_f32_e32 v235, v20, v20
	v_cvt_pk_bf16_f32 v22, v22, v23
	v_add_f32_e32 v234, v234, v235
	v_cvt_pk_bf16_f32 v23, v24, v25
	v_add_f32_e32 v232, v232, v234
	v_cvt_pk_bf16_f32 v24, v18, v19
	v_cvt_pk_bf16_f32 v25, v20, v21
	global_store_dwordx4 v[250:251], v[22:25], off
	v_mul_f32_e32 v240, v33, v33
	v_mul_f32_e32 v241, v35, v35
	v_fmac_f32_e32 v240, v32, v32
	v_fmac_f32_e32 v241, v34, v34
	v_mul_f32_e32 v242, v29, v29
	v_mul_f32_e32 v243, v31, v31
	v_add_f32_e32 v240, v240, v241
	v_fmac_f32_e32 v242, v28, v28
	v_fmac_f32_e32 v243, v30, v30
	v_cvt_pk_bf16_f32 v32, v32, v33
	v_add_f32_e32 v242, v242, v243
	v_cvt_pk_bf16_f32 v33, v34, v35
	v_add_f32_e32 v240, v240, v242
	v_cvt_pk_bf16_f32 v34, v28, v29
	v_cvt_pk_bf16_f32 v35, v30, v31
	global_store_dwordx4 v[250:251], v[32:35], off offset:256
	v_add_f32_e32 v18, v232, v240
	v_lshl_add_u64 v[250:251], v[250:251], 0, s[6:7]
	s_waitcnt vmcnt(6)
	v_pk_add_f32 v[6:7], v[6:7], v[148:149]
	v_pk_add_f32 v[8:9], v[8:9], v[150:151]
	v_pk_add_f32 v[2:3], v[2:3], v[152:153]
	v_pk_add_f32 v[4:5], v[4:5], v[154:155]
	v_pk_add_f32 v[14:15], v[14:15], v[156:157]
	v_pk_add_f32 v[16:17], v[16:17], v[158:159]
	v_pk_add_f32 v[10:11], v[10:11], v[160:161]
	v_pk_add_f32 v[12:13], v[12:13], v[162:163]
	v_mul_f32_e32 v148, v7, v7
	v_mul_f32_e32 v149, v9, v9
	v_fmac_f32_e32 v148, v6, v6
	v_fmac_f32_e32 v149, v8, v8
	v_mul_f32_e32 v150, v3, v3
	v_mul_f32_e32 v151, v5, v5
	v_add_f32_e32 v148, v148, v149
	v_fmac_f32_e32 v150, v2, v2
	v_fmac_f32_e32 v151, v4, v4
	v_cvt_pk_bf16_f32 v6, v6, v7
	v_add_f32_e32 v150, v150, v151
	v_cvt_pk_bf16_f32 v7, v8, v9
	v_add_f32_e32 v148, v148, v150
	v_cvt_pk_bf16_f32 v8, v2, v3
	v_cvt_pk_bf16_f32 v9, v4, v5
	global_store_dwordx4 v[250:251], v[6:9], off
	v_mul_f32_e32 v156, v15, v15
	v_mul_f32_e32 v157, v17, v17
	v_fmac_f32_e32 v156, v14, v14
	v_fmac_f32_e32 v157, v16, v16
	v_mul_f32_e32 v158, v11, v11
	v_mul_f32_e32 v159, v13, v13
	v_add_f32_e32 v156, v156, v157
	v_fmac_f32_e32 v158, v10, v10
	v_fmac_f32_e32 v159, v12, v12
	v_cvt_pk_bf16_f32 v14, v14, v15
	v_add_f32_e32 v158, v158, v159
	v_cvt_pk_bf16_f32 v15, v16, v17
	v_add_f32_e32 v156, v156, v158
	v_cvt_pk_bf16_f32 v16, v10, v11
	v_cvt_pk_bf16_f32 v17, v12, v13
	global_store_dwordx4 v[250:251], v[14:17], off offset:256
	v_add_f32_e32 v2, v148, v156
	ds_bpermute_b32 v125, v132, v124
	ds_bpermute_b32 v101, v132, v100
	ds_bpermute_b32 v85, v132, v84
	ds_bpermute_b32 v45, v132, v44
	ds_bpermute_b32 v61, v132, v60
	ds_bpermute_b32 v37, v132, v36
	ds_bpermute_b32 v19, v132, v18
	ds_bpermute_b32 v3, v132, v2
	s_waitcnt lgkmcnt(0)
	v_add_f32_e32 v124, v124, v125
	v_add_f32_e32 v100, v100, v101
	v_add_f32_e32 v84, v84, v85
	v_add_f32_e32 v44, v44, v45
	v_add_f32_e32 v60, v60, v61
	v_add_f32_e32 v36, v36, v37
	v_add_f32_e32 v18, v18, v19
	v_add_f32_e32 v2, v2, v3
	ds_bpermute_b32 v125, v133, v124
	ds_bpermute_b32 v101, v133, v100
	ds_bpermute_b32 v85, v133, v84
	ds_bpermute_b32 v45, v133, v44
	ds_bpermute_b32 v61, v133, v60
	ds_bpermute_b32 v37, v133, v36
	ds_bpermute_b32 v19, v133, v18
	ds_bpermute_b32 v3, v133, v2
	s_and_saveexec_b64 s[0:1], s[4:5]
	s_cbranch_execz .LBB0_947
	s_waitcnt lgkmcnt(0)
	v_add_f32_e32 v124, v124, v125
	v_add_f32_e32 v100, v100, v101
	v_add_f32_e32 v84, v84, v85
	v_add_f32_e32 v44, v44, v45
	v_add_f32_e32 v60, v60, v61
	v_add_f32_e32 v36, v36, v37
	v_add_f32_e32 v18, v18, v19
	v_add_f32_e32 v2, v2, v3
	global_atomic_add_f32 v[252:253], v124, off
	global_atomic_add_f32 v[252:253], v100, off offset:64
	global_atomic_add_f32 v[252:253], v84, off offset:128
	global_atomic_add_f32 v[252:253], v44, off offset:192
	global_atomic_add_f32 v[252:253], v60, off offset:512
	global_atomic_add_f32 v[252:253], v36, off offset:576
	global_atomic_add_f32 v[252:253], v18, off offset:640
	global_atomic_add_f32 v[252:253], v2, off offset:704
